# added: 64-bit moves to zero the 128 accumulators at each GEMM unit start (6 GEMM instances)
# speedup vs baseline: 1.0011x; 1.0011x over previous
.LBB0_213:
	s_ashr_i32 s45, s44, 31
	s_lshl_b64 s[2:3], s[44:45], 19
	s_add_u32 s46, s18, s2
	s_addc_u32 s47, s19, s3
	s_and_b64 s[2:3], s[38:39], exec
	s_cselect_b32 s2, s47, s53
	s_cselect_b32 s3, s46, s52
	s_ashr_i32 s43, s42, 31
	s_lshl_b64 s[24:25], s[42:43], 19
	s_add_u32 s48, s97, s24
	v_readlane_b32 s13, v255, 8
	s_addc_u32 s49, s13, s25
	s_and_b64 s[24:25], s[38:39], exec
	s_cselect_b32 s13, s49, s71
	s_cselect_b32 s16, s48, s70
	s_add_u32 s30, s52, 0x40080
	s_addc_u32 s31, s53, 0
	s_add_u32 s24, s70, 0x100
	s_addc_u32 s25, s71, 0
	s_mov_b32 s26, -2
	v_mov_b64_e32 v[2:3], 0
	v_mov_b64_e32 v[4:5], 0
	v_mov_b64_e32 v[6:7], 0
	v_mov_b64_e32 v[8:9], 0
	v_mov_b64_e32 v[10:11], 0
	v_mov_b64_e32 v[12:13], 0
	v_mov_b64_e32 v[14:15], 0
	v_mov_b64_e32 v[16:17], 0
	v_mov_b64_e32 v[18:19], 0
	v_mov_b64_e32 v[20:21], 0
	v_mov_b64_e32 v[22:23], 0
	v_mov_b64_e32 v[24:25], 0
	v_mov_b64_e32 v[26:27], 0
	v_mov_b64_e32 v[28:29], 0
	v_mov_b64_e32 v[30:31], 0
	v_mov_b64_e32 v[32:33], 0
	v_mov_b64_e32 v[34:35], 0
	v_mov_b64_e32 v[36:37], 0
	v_mov_b64_e32 v[38:39], 0
	v_mov_b64_e32 v[40:41], 0
	v_mov_b64_e32 v[42:43], 0
	v_mov_b64_e32 v[44:45], 0
	v_mov_b64_e32 v[46:47], 0
	v_mov_b64_e32 v[48:49], 0
	v_mov_b64_e32 v[50:51], 0
	v_mov_b64_e32 v[52:53], 0
	v_mov_b64_e32 v[54:55], 0
	v_mov_b64_e32 v[56:57], 0
	v_mov_b64_e32 v[58:59], 0
	v_mov_b64_e32 v[60:61], 0
	v_mov_b64_e32 v[62:63], 0
	v_mov_b64_e32 v[64:65], 0
	v_mov_b64_e32 v[66:67], 0
	v_mov_b64_e32 v[68:69], 0
	v_mov_b64_e32 v[70:71], 0
	v_mov_b64_e32 v[72:73], 0
	v_mov_b64_e32 v[74:75], 0
	v_mov_b64_e32 v[76:77], 0
	v_mov_b64_e32 v[78:79], 0
	v_mov_b64_e32 v[80:81], 0
	v_mov_b64_e32 v[82:83], 0
	v_mov_b64_e32 v[84:85], 0
	v_mov_b64_e32 v[86:87], 0
	v_mov_b64_e32 v[88:89], 0
	v_mov_b64_e32 v[90:91], 0
	v_mov_b64_e32 v[92:93], 0
	v_mov_b64_e32 v[94:95], 0
	v_mov_b64_e32 v[96:97], 0
	v_mov_b64_e32 v[98:99], 0
	v_mov_b64_e32 v[100:101], 0
	v_mov_b64_e32 v[102:103], 0
	v_mov_b64_e32 v[104:105], 0
	v_mov_b64_e32 v[106:107], 0
	v_mov_b64_e32 v[108:109], 0
	v_mov_b64_e32 v[110:111], 0
	v_mov_b64_e32 v[112:113], 0
	v_mov_b64_e32 v[114:115], 0
	v_mov_b64_e32 v[116:117], 0
	v_mov_b64_e32 v[118:119], 0
	v_mov_b64_e32 v[120:121], 0
	v_mov_b64_e32 v[122:123], 0
	v_mov_b64_e32 v[124:125], 0
	v_mov_b64_e32 v[126:127], 0
	v_mov_b64_e32 v[128:129], 0

.LBB0_694:
	s_ashr_i32 s45, s44, 31
	s_lshl_b64 s[24:25], s[44:45], 19
	s_add_u32 s46, s17, s24
	s_addc_u32 s47, s18, s25
	s_and_b64 s[24:25], s[42:43], exec
	s_cselect_b32 s3, s47, s13
	s_cselect_b32 s16, s46, s12
	s_ashr_i32 s35, s34, 31
	s_lshl_b64 s[24:25], s[34:35], 19
	s_add_u32 s48, s19, s24
	s_addc_u32 s49, s29, s25
	s_and_b64 s[24:25], s[42:43], exec
	s_cselect_b32 s24, s49, s31
	s_cselect_b32 s25, s48, s30
	s_add_u32 s12, s12, 0x40080
	s_addc_u32 s13, s13, 0
	s_add_u32 s26, s30, 0x100
	s_addc_u32 s28, s31, 0
	s_mov_b32 s35, -2
	s_waitcnt vmcnt(0)
	v_mov_b64_e32 v[2:3], 0
	v_mov_b64_e32 v[4:5], 0
	v_mov_b64_e32 v[6:7], 0
	v_mov_b64_e32 v[8:9], 0
	v_mov_b64_e32 v[10:11], 0
	v_mov_b64_e32 v[12:13], 0
	v_mov_b64_e32 v[14:15], 0
	v_mov_b64_e32 v[16:17], 0
	v_mov_b64_e32 v[18:19], 0
	v_mov_b64_e32 v[20:21], 0
	v_mov_b64_e32 v[22:23], 0
	v_mov_b64_e32 v[24:25], 0
	v_mov_b64_e32 v[26:27], 0
	v_mov_b64_e32 v[28:29], 0
	v_mov_b64_e32 v[30:31], 0
	v_mov_b64_e32 v[32:33], 0
	v_mov_b64_e32 v[34:35], 0
	v_mov_b64_e32 v[36:37], 0
	v_mov_b64_e32 v[38:39], 0
	v_mov_b64_e32 v[40:41], 0
	v_mov_b64_e32 v[42:43], 0
	v_mov_b64_e32 v[44:45], 0
	v_mov_b64_e32 v[46:47], 0
	v_mov_b64_e32 v[48:49], 0
	v_mov_b64_e32 v[50:51], 0
	v_mov_b64_e32 v[52:53], 0
	v_mov_b64_e32 v[54:55], 0
	v_mov_b64_e32 v[56:57], 0
	v_mov_b64_e32 v[58:59], 0
	v_mov_b64_e32 v[60:61], 0
	v_mov_b64_e32 v[62:63], 0
	v_mov_b64_e32 v[64:65], 0
	v_mov_b64_e32 v[66:67], 0
	v_mov_b64_e32 v[68:69], 0
	v_mov_b64_e32 v[70:71], 0
	v_mov_b64_e32 v[72:73], 0
	v_mov_b64_e32 v[74:75], 0
	v_mov_b64_e32 v[76:77], 0
	v_mov_b64_e32 v[78:79], 0
	v_mov_b64_e32 v[80:81], 0
	v_mov_b64_e32 v[82:83], 0
	v_mov_b64_e32 v[84:85], 0
	v_mov_b64_e32 v[86:87], 0
	v_mov_b64_e32 v[88:89], 0
	v_mov_b64_e32 v[90:91], 0
	v_mov_b64_e32 v[92:93], 0
	v_mov_b64_e32 v[94:95], 0
	v_mov_b64_e32 v[96:97], 0
	v_mov_b64_e32 v[98:99], 0
	v_mov_b64_e32 v[100:101], 0
	v_mov_b64_e32 v[102:103], 0
	v_mov_b64_e32 v[104:105], 0
	v_mov_b64_e32 v[106:107], 0
	v_mov_b64_e32 v[108:109], 0
	v_mov_b64_e32 v[110:111], 0
	v_mov_b64_e32 v[112:113], 0
	v_mov_b64_e32 v[114:115], 0
	v_mov_b64_e32 v[116:117], 0
	v_mov_b64_e32 v[118:119], 0
	v_mov_b64_e32 v[120:121], 0
	v_mov_b64_e32 v[122:123], 0
	v_mov_b64_e32 v[124:125], 0
	v_mov_b64_e32 v[126:127], 0
	v_mov_b64_e32 v[128:129], 0

.LBB0_791:
	s_ashr_i32 s15, s14, 31
	s_lshl_b64 s[20:21], s[14:15], 19
	s_add_u32 s20, s2, s20
	s_addc_u32 s21, s3, s21
	s_and_b64 s[30:31], s[4:5], exec
	s_cselect_b32 s15, s21, s35
	s_cselect_b32 s46, s20, s34
	s_ashr_i32 s13, s12, 31
	s_lshl_b64 s[30:31], s[12:13], 19
	s_add_u32 s30, s16, s30
	s_addc_u32 s31, s17, s31
	s_and_b64 s[40:41], s[4:5], exec
	s_cselect_b32 s13, s31, s37
	s_cselect_b32 s47, s30, s36
	s_add_u32 s34, s34, 0x40080
	s_addc_u32 s35, s35, 0
	s_add_u32 s48, s36, 0x100
	s_addc_u32 s49, s37, 0
	s_mov_b32 s50, -2
	v_mov_b64_e32 v[2:3], 0
	v_mov_b64_e32 v[4:5], 0
	v_mov_b64_e32 v[6:7], 0
	v_mov_b64_e32 v[8:9], 0
	v_mov_b64_e32 v[10:11], 0
	v_mov_b64_e32 v[12:13], 0
	v_mov_b64_e32 v[14:15], 0
	v_mov_b64_e32 v[16:17], 0
	v_mov_b64_e32 v[18:19], 0
	v_mov_b64_e32 v[20:21], 0
	v_mov_b64_e32 v[22:23], 0
	v_mov_b64_e32 v[24:25], 0
	v_mov_b64_e32 v[26:27], 0
	v_mov_b64_e32 v[28:29], 0
	v_mov_b64_e32 v[30:31], 0
	v_mov_b64_e32 v[32:33], 0
	v_mov_b64_e32 v[34:35], 0
	v_mov_b64_e32 v[36:37], 0
	v_mov_b64_e32 v[38:39], 0
	v_mov_b64_e32 v[40:41], 0
	v_mov_b64_e32 v[42:43], 0
	v_mov_b64_e32 v[44:45], 0
	v_mov_b64_e32 v[46:47], 0
	v_mov_b64_e32 v[48:49], 0
	v_mov_b64_e32 v[50:51], 0
	v_mov_b64_e32 v[52:53], 0
	v_mov_b64_e32 v[54:55], 0
	v_mov_b64_e32 v[56:57], 0
	v_mov_b64_e32 v[58:59], 0
	v_mov_b64_e32 v[60:61], 0
	v_mov_b64_e32 v[62:63], 0
	v_mov_b64_e32 v[64:65], 0
	v_mov_b64_e32 v[66:67], 0
	v_mov_b64_e32 v[68:69], 0
	v_mov_b64_e32 v[70:71], 0
	v_mov_b64_e32 v[72:73], 0
	v_mov_b64_e32 v[74:75], 0
	v_mov_b64_e32 v[76:77], 0
	v_mov_b64_e32 v[78:79], 0
	v_mov_b64_e32 v[80:81], 0
	v_mov_b64_e32 v[82:83], 0
	v_mov_b64_e32 v[84:85], 0
	v_mov_b64_e32 v[86:87], 0
	v_mov_b64_e32 v[88:89], 0
	v_mov_b64_e32 v[90:91], 0
	v_mov_b64_e32 v[92:93], 0
	v_mov_b64_e32 v[94:95], 0
	v_mov_b64_e32 v[96:97], 0
	v_mov_b64_e32 v[98:99], 0
	v_mov_b64_e32 v[100:101], 0
	v_mov_b64_e32 v[102:103], 0
	v_mov_b64_e32 v[104:105], 0
	v_mov_b64_e32 v[106:107], 0
	v_mov_b64_e32 v[108:109], 0
	v_mov_b64_e32 v[110:111], 0
	v_mov_b64_e32 v[112:113], 0
	v_mov_b64_e32 v[114:115], 0
	v_mov_b64_e32 v[116:117], 0
	v_mov_b64_e32 v[118:119], 0
	v_mov_b64_e32 v[120:121], 0
	v_mov_b64_e32 v[122:123], 0
	v_mov_b64_e32 v[124:125], 0
	v_mov_b64_e32 v[126:127], 0
	v_mov_b64_e32 v[128:129], 0

.LBB0_863:
	s_ashr_i32 s45, s44, 31
	s_lshl_b64 s[24:25], s[44:45], 21
	s_add_u32 s46, s17, s24
	s_addc_u32 s47, s18, s25
	s_and_b64 s[24:25], s[42:43], exec
	s_cselect_b32 s3, s47, s13
	s_cselect_b32 s16, s46, s12
	s_ashr_i32 s35, s34, 31
	s_lshl_b64 s[24:25], s[34:35], 21
	s_add_u32 s48, s19, s24
	s_addc_u32 s49, s29, s25
	s_and_b64 s[24:25], s[42:43], exec
	s_cselect_b32 s24, s49, s31
	s_cselect_b32 s25, s48, s30
	s_add_u32 s12, s12, 0x100080
	s_addc_u32 s13, s13, 0
	s_add_u32 s26, s30, 0x100
	s_addc_u32 s28, s31, 0
	s_mov_b32 s35, -2
	v_mov_b64_e32 v[2:3], 0
	v_mov_b64_e32 v[4:5], 0
	v_mov_b64_e32 v[6:7], 0
	v_mov_b64_e32 v[8:9], 0
	v_mov_b64_e32 v[10:11], 0
	v_mov_b64_e32 v[12:13], 0
	v_mov_b64_e32 v[14:15], 0
	v_mov_b64_e32 v[16:17], 0
	v_mov_b64_e32 v[18:19], 0
	v_mov_b64_e32 v[20:21], 0
	v_mov_b64_e32 v[22:23], 0
	v_mov_b64_e32 v[24:25], 0
	v_mov_b64_e32 v[26:27], 0
	v_mov_b64_e32 v[28:29], 0
	v_mov_b64_e32 v[30:31], 0
	v_mov_b64_e32 v[32:33], 0
	v_mov_b64_e32 v[34:35], 0
	v_mov_b64_e32 v[36:37], 0
	v_mov_b64_e32 v[38:39], 0
	v_mov_b64_e32 v[40:41], 0
	v_mov_b64_e32 v[42:43], 0
	v_mov_b64_e32 v[44:45], 0
	v_mov_b64_e32 v[46:47], 0
	v_mov_b64_e32 v[48:49], 0
	v_mov_b64_e32 v[50:51], 0
	v_mov_b64_e32 v[52:53], 0
	v_mov_b64_e32 v[54:55], 0
	v_mov_b64_e32 v[56:57], 0
	v_mov_b64_e32 v[58:59], 0
	v_mov_b64_e32 v[60:61], 0
	v_mov_b64_e32 v[62:63], 0
	v_mov_b64_e32 v[64:65], 0
	v_mov_b64_e32 v[66:67], 0
	v_mov_b64_e32 v[68:69], 0
	v_mov_b64_e32 v[70:71], 0
	v_mov_b64_e32 v[72:73], 0
	v_mov_b64_e32 v[74:75], 0
	v_mov_b64_e32 v[76:77], 0
	v_mov_b64_e32 v[78:79], 0
	v_mov_b64_e32 v[80:81], 0
	v_mov_b64_e32 v[82:83], 0
	v_mov_b64_e32 v[84:85], 0
	v_mov_b64_e32 v[86:87], 0
	v_mov_b64_e32 v[88:89], 0
	v_mov_b64_e32 v[90:91], 0
	v_mov_b64_e32 v[92:93], 0
	v_mov_b64_e32 v[94:95], 0
	v_mov_b64_e32 v[96:97], 0
	v_mov_b64_e32 v[98:99], 0
	v_mov_b64_e32 v[100:101], 0
	v_mov_b64_e32 v[102:103], 0
	v_mov_b64_e32 v[104:105], 0
	v_mov_b64_e32 v[106:107], 0
	v_mov_b64_e32 v[108:109], 0
	v_mov_b64_e32 v[110:111], 0
	v_mov_b64_e32 v[112:113], 0
	v_mov_b64_e32 v[114:115], 0
	v_mov_b64_e32 v[116:117], 0
	v_mov_b64_e32 v[118:119], 0
	v_mov_b64_e32 v[120:121], 0
	v_mov_b64_e32 v[122:123], 0
	v_mov_b64_e32 v[124:125], 0
	v_mov_b64_e32 v[126:127], 0
	v_mov_b64_e32 v[128:129], 0

.LBB0_955:
	v_mov_b32_e32 v125, 0
	s_andn2_b64 vcc, exec, s[20:21]
	v_mov_b32_e32 v124, v125
	v_mov_b32_e32 v123, v125
	v_mov_b32_e32 v122, v125
	v_mov_b32_e32 v129, v125
	v_mov_b32_e32 v128, v125
	v_mov_b32_e32 v127, v125
	v_mov_b32_e32 v126, v125
	v_mov_b32_e32 v113, v125
	v_mov_b32_e32 v112, v125
	v_mov_b32_e32 v111, v125
	v_mov_b32_e32 v110, v125
	v_mov_b32_e32 v109, v125
	v_mov_b32_e32 v108, v125
	v_mov_b32_e32 v107, v125
	v_mov_b32_e32 v106, v125
	v_mov_b32_e32 v97, v125
	v_mov_b32_e32 v96, v125
	v_mov_b32_e32 v95, v125
	v_mov_b32_e32 v94, v125
	v_mov_b32_e32 v93, v125
	v_mov_b32_e32 v92, v125
	v_mov_b32_e32 v91, v125
	v_mov_b32_e32 v90, v125
	v_mov_b32_e32 v81, v125
	v_mov_b32_e32 v80, v125
	v_mov_b32_e32 v79, v125
	v_mov_b32_e32 v78, v125
	v_mov_b32_e32 v77, v125
	v_mov_b32_e32 v76, v125
	v_mov_b32_e32 v75, v125
	v_mov_b32_e32 v74, v125
	v_mov_b32_e32 v121, v125
	v_mov_b32_e32 v120, v125
	v_mov_b32_e32 v119, v125
	v_mov_b32_e32 v118, v125
	v_mov_b32_e32 v117, v125
	v_mov_b32_e32 v116, v125
	v_mov_b32_e32 v115, v125
	v_mov_b32_e32 v114, v125
	v_mov_b32_e32 v105, v125
	v_mov_b32_e32 v104, v125
	v_mov_b32_e32 v103, v125
	v_mov_b32_e32 v102, v125
	v_mov_b32_e32 v101, v125
	v_mov_b32_e32 v100, v125
	v_mov_b32_e32 v99, v125
	v_mov_b32_e32 v98, v125
	v_mov_b32_e32 v89, v125
	v_mov_b32_e32 v88, v125
	v_mov_b32_e32 v87, v125
	v_mov_b32_e32 v86, v125
	v_mov_b32_e32 v85, v125
	v_mov_b32_e32 v84, v125
	v_mov_b32_e32 v83, v125
	v_mov_b32_e32 v82, v125
	v_mov_b32_e32 v73, v125
	v_mov_b32_e32 v72, v125
	v_mov_b32_e32 v71, v125
	v_mov_b32_e32 v70, v125
	v_mov_b32_e32 v69, v125
	v_mov_b32_e32 v68, v125
	v_mov_b32_e32 v67, v125
	v_mov_b32_e32 v66, v125
	v_mov_b32_e32 v65, v125
	v_mov_b32_e32 v64, v125
	v_mov_b32_e32 v63, v125
	v_mov_b32_e32 v62, v125
	v_mov_b32_e32 v61, v125
	v_mov_b32_e32 v60, v125
	v_mov_b32_e32 v59, v125
	v_mov_b32_e32 v58, v125
	v_mov_b32_e32 v49, v125
	v_mov_b32_e32 v48, v125
	v_mov_b32_e32 v47, v125
	v_mov_b32_e32 v46, v125
	v_mov_b32_e32 v45, v125
	v_mov_b32_e32 v44, v125
	v_mov_b32_e32 v43, v125
	v_mov_b32_e32 v42, v125
	v_mov_b32_e32 v33, v125
	v_mov_b32_e32 v32, v125
	v_mov_b32_e32 v31, v125
	v_mov_b32_e32 v30, v125
	v_mov_b32_e32 v29, v125
	v_mov_b32_e32 v28, v125
	v_mov_b32_e32 v27, v125
	v_mov_b32_e32 v26, v125
	v_mov_b32_e32 v17, v125
	v_mov_b32_e32 v16, v125
	v_mov_b32_e32 v15, v125
	v_mov_b32_e32 v14, v125
	v_mov_b32_e32 v13, v125
	v_mov_b32_e32 v12, v125
	v_mov_b32_e32 v11, v125
	v_mov_b32_e32 v10, v125
	v_mov_b32_e32 v57, v125
	v_mov_b32_e32 v56, v125
	v_mov_b32_e32 v55, v125
	v_mov_b32_e32 v54, v125
	v_mov_b32_e32 v53, v125
	v_mov_b32_e32 v52, v125
	v_mov_b32_e32 v51, v125
	v_mov_b32_e32 v50, v125
	v_mov_b32_e32 v41, v125
	v_mov_b32_e32 v40, v125
	v_mov_b32_e32 v39, v125
	v_mov_b32_e32 v38, v125
	v_mov_b32_e32 v37, v125
	v_mov_b32_e32 v36, v125
	v_mov_b32_e32 v35, v125
	v_mov_b32_e32 v34, v125
	v_mov_b32_e32 v25, v125
	v_mov_b32_e32 v24, v125
	v_mov_b32_e32 v23, v125
	v_mov_b32_e32 v22, v125
	v_mov_b32_e32 v21, v125
	v_mov_b32_e32 v20, v125
	v_mov_b32_e32 v19, v125
	v_mov_b32_e32 v18, v125
	v_mov_b32_e32 v9, v125
	v_mov_b32_e32 v8, v125
	v_mov_b32_e32 v7, v125
	v_mov_b32_e32 v6, v125
	v_mov_b32_e32 v5, v125
	v_mov_b32_e32 v4, v125
	v_mov_b32_e32 v3, v125
	v_mov_b32_e32 v2, v125
	s_cbranch_vccnz .LBB0_958
	s_add_u32 s36, s36, 0x80
	s_addc_u32 s37, s37, 0
	s_add_u32 s50, s40, 0x100
	s_addc_u32 s51, s41, 0
	s_mov_b32 s40, 0
	v_mov_b64_e32 v[2:3], 0
	v_mov_b64_e32 v[4:5], 0
	v_mov_b64_e32 v[6:7], 0
	v_mov_b64_e32 v[8:9], 0
	v_mov_b64_e32 v[10:11], 0
	v_mov_b64_e32 v[12:13], 0
	v_mov_b64_e32 v[14:15], 0
	v_mov_b64_e32 v[16:17], 0
	v_mov_b64_e32 v[18:19], 0
	v_mov_b64_e32 v[20:21], 0
	v_mov_b64_e32 v[22:23], 0
	v_mov_b64_e32 v[24:25], 0
	v_mov_b64_e32 v[26:27], 0
	v_mov_b64_e32 v[28:29], 0
	v_mov_b64_e32 v[30:31], 0
	v_mov_b64_e32 v[32:33], 0
	v_mov_b64_e32 v[34:35], 0
	v_mov_b64_e32 v[36:37], 0
	v_mov_b64_e32 v[38:39], 0
	v_mov_b64_e32 v[40:41], 0
	v_mov_b64_e32 v[42:43], 0
	v_mov_b64_e32 v[44:45], 0
	v_mov_b64_e32 v[46:47], 0
	v_mov_b64_e32 v[48:49], 0
	v_mov_b64_e32 v[50:51], 0
	v_mov_b64_e32 v[52:53], 0
	v_mov_b64_e32 v[54:55], 0
	v_mov_b64_e32 v[56:57], 0
	v_mov_b64_e32 v[58:59], 0
	v_mov_b64_e32 v[60:61], 0
	v_mov_b64_e32 v[62:63], 0
	v_mov_b64_e32 v[64:65], 0
	v_mov_b64_e32 v[66:67], 0
	v_mov_b64_e32 v[68:69], 0
	v_mov_b64_e32 v[70:71], 0
	v_mov_b64_e32 v[72:73], 0
	v_mov_b64_e32 v[74:75], 0
	v_mov_b64_e32 v[76:77], 0
	v_mov_b64_e32 v[78:79], 0
	v_mov_b64_e32 v[80:81], 0
	v_mov_b64_e32 v[82:83], 0
	v_mov_b64_e32 v[84:85], 0
	v_mov_b64_e32 v[86:87], 0
	v_mov_b64_e32 v[88:89], 0
	v_mov_b64_e32 v[90:91], 0
	v_mov_b64_e32 v[92:93], 0
	v_mov_b64_e32 v[94:95], 0
	v_mov_b64_e32 v[96:97], 0
	v_mov_b64_e32 v[98:99], 0
	v_mov_b64_e32 v[100:101], 0
	v_mov_b64_e32 v[102:103], 0
	v_mov_b64_e32 v[104:105], 0
	v_mov_b64_e32 v[106:107], 0
	v_mov_b64_e32 v[108:109], 0
	v_mov_b64_e32 v[110:111], 0
	v_mov_b64_e32 v[112:113], 0
	v_mov_b64_e32 v[114:115], 0
	v_mov_b64_e32 v[116:117], 0
	v_mov_b64_e32 v[118:119], 0
	v_mov_b64_e32 v[120:121], 0
	v_mov_b64_e32 v[122:123], 0
	v_mov_b64_e32 v[124:125], 0
	v_mov_b64_e32 v[126:127], 0
	v_mov_b64_e32 v[128:129], 0

.LBB0_985:
	s_ashr_i32 s21, s20, 31
	s_lshl_b64 s[18:19], s[20:21], 19
	s_add_u32 s34, s29, s18
	s_addc_u32 s35, s44, s19
	s_and_b64 s[18:19], s[40:41], exec
	s_cselect_b32 s3, s35, s13
	s_cselect_b32 s16, s34, s12
	s_ashr_i32 s15, s14, 31
	s_lshl_b64 s[18:19], s[14:15], 19
	s_add_u32 s42, s45, s18
	s_addc_u32 s43, s46, s19
	s_and_b64 s[18:19], s[40:41], exec
	s_cselect_b32 s15, s43, s31
	s_cselect_b32 s18, s42, s30
	s_add_u32 s12, s12, 0x40080
	s_addc_u32 s13, s13, 0
	s_add_u32 s19, s30, 0x100
	s_addc_u32 s21, s31, 0
	s_mov_b32 s24, -2
	v_mov_b64_e32 v[2:3], 0
	v_mov_b64_e32 v[4:5], 0
	v_mov_b64_e32 v[6:7], 0
	v_mov_b64_e32 v[8:9], 0
	v_mov_b64_e32 v[10:11], 0
	v_mov_b64_e32 v[12:13], 0
	v_mov_b64_e32 v[14:15], 0
	v_mov_b64_e32 v[16:17], 0
	v_mov_b64_e32 v[18:19], 0
	v_mov_b64_e32 v[20:21], 0
	v_mov_b64_e32 v[22:23], 0
	v_mov_b64_e32 v[24:25], 0
	v_mov_b64_e32 v[26:27], 0
	v_mov_b64_e32 v[28:29], 0
	v_mov_b64_e32 v[30:31], 0
	v_mov_b64_e32 v[32:33], 0
	v_mov_b64_e32 v[34:35], 0
	v_mov_b64_e32 v[36:37], 0
	v_mov_b64_e32 v[38:39], 0
	v_mov_b64_e32 v[40:41], 0
	v_mov_b64_e32 v[42:43], 0
	v_mov_b64_e32 v[44:45], 0
	v_mov_b64_e32 v[46:47], 0
	v_mov_b64_e32 v[48:49], 0
	v_mov_b64_e32 v[50:51], 0
	v_mov_b64_e32 v[52:53], 0
	v_mov_b64_e32 v[54:55], 0
	v_mov_b64_e32 v[56:57], 0
	v_mov_b64_e32 v[58:59], 0
	v_mov_b64_e32 v[60:61], 0
	v_mov_b64_e32 v[62:63], 0
	v_mov_b64_e32 v[64:65], 0
	v_mov_b64_e32 v[66:67], 0
	v_mov_b64_e32 v[68:69], 0
	v_mov_b64_e32 v[70:71], 0
	v_mov_b64_e32 v[72:73], 0
	v_mov_b64_e32 v[74:75], 0
	v_mov_b64_e32 v[76:77], 0
	v_mov_b64_e32 v[78:79], 0
	v_mov_b64_e32 v[80:81], 0
	v_mov_b64_e32 v[82:83], 0
	v_mov_b64_e32 v[84:85], 0
	v_mov_b64_e32 v[86:87], 0
	v_mov_b64_e32 v[88:89], 0
	v_mov_b64_e32 v[90:91], 0
	v_mov_b64_e32 v[92:93], 0
	v_mov_b64_e32 v[94:95], 0
	v_mov_b64_e32 v[96:97], 0
	v_mov_b64_e32 v[98:99], 0
	v_mov_b64_e32 v[100:101], 0
	v_mov_b64_e32 v[102:103], 0
	v_mov_b64_e32 v[104:105], 0
	v_mov_b64_e32 v[106:107], 0
	v_mov_b64_e32 v[108:109], 0
	v_mov_b64_e32 v[110:111], 0
	v_mov_b64_e32 v[112:113], 0
	v_mov_b64_e32 v[114:115], 0
	v_mov_b64_e32 v[116:117], 0
	v_mov_b64_e32 v[118:119], 0
	v_mov_b64_e32 v[120:121], 0
	v_mov_b64_e32 v[122:123], 0
	v_mov_b64_e32 v[124:125], 0
	v_mov_b64_e32 v[126:127], 0
	v_mov_b64_e32 v[128:129], 0
